# v15 + 64-byte alignment of the five steady-state K-loop bodies (code placement)
# speedup vs baseline: 1.0028x; 1.0028x over previous
.LBB0_260:
	s_ashr_i32 s65, s64, 31
	s_lshl_b64 s[22:23], s[64:65], 20
	s_add_u32 s62, s79, s22
	s_addc_u32 s63, s28, s23
	s_and_b64 s[22:23], s[4:5], exec
	s_cselect_b32 s22, s63, s77
	s_cselect_b32 s23, s62, s76
	s_ashr_i32 s49, s48, 31
	s_lshl_b64 s[70:71], s[48:49], 20
	s_add_u32 s70, s8, s70
	s_addc_u32 s71, s9, s71
	s_and_b64 s[90:91], s[4:5], exec
	s_cselect_b32 s49, s71, s85
	s_cselect_b32 s57, s70, s84
	s_ashr_i32 s51, s50, 31
	s_lshl_b32 s90, s44, 8
	s_lshl_b64 vcc, s[50:51], 10
	s_ashr_i32 s0, s50, 5
	s_ashr_i32 s91, s90, 31
	s_add_u32 s76, s76, 0x80080
	v_lshl_add_u64 v[2:3], s[90:91], 2, v[134:135]
	v_mov_b32_e32 v4, 0x6000
	s_addc_u32 s77, s77, 0
	v_lshl_add_u64 v[142:143], v[136:137], 0, vcc
	v_mad_i64_i32 v[144:145], vcc, s0, v4, v[2:3]
	s_add_u32 s51, s84, 0x100
	s_addc_u32 s58, s85, 0
	s_mov_b32 s65, -2
	s_branch .LBB0_262
	.p2align	6

.LBB0_284:
	s_ashr_i32 s49, s48, 31
	s_lshl_b64 s[22:23], s[48:49], 20
	s_add_u32 s50, s79, s22
	s_addc_u32 s51, s28, s23
	s_and_b64 s[22:23], s[4:5], exec
	s_cselect_b32 s21, s51, s77
	s_cselect_b32 s22, s50, s76
	s_ashr_i32 s39, s38, 31
	s_lshl_b64 s[62:63], s[38:39], 20
	s_add_u32 s62, s29, s62
	s_addc_u32 s63, s31, s63
	s_and_b64 s[64:65], s[4:5], exec
	s_cselect_b32 s23, s63, s71
	s_cselect_b32 s39, s62, s70
	s_ashr_i32 s7, s6, 31
	s_lshl_b32 s64, s40, 8
	s_lshl_b64 vcc, s[6:7], 10
	s_ashr_i32 s0, s6, 5
	s_ashr_i32 s65, s64, 31
	s_add_u32 s76, s76, 0x80080
	v_lshl_add_u64 v[2:3], s[64:65], 2, v[166:167]
	v_mov_b32_e32 v4, 0x5800
	s_addc_u32 s77, s77, 0
	v_lshl_add_u64 v[130:131], v[168:169], 0, vcc
	v_mad_i64_i32 v[132:133], vcc, s0, v4, v[2:3]
	s_add_u32 s7, s70, 0x100
	s_addc_u32 s41, s71, 0
	s_mov_b32 s43, -2
	s_branch .LBB0_286
	.p2align	6

.LBB0_508:
	s_ashr_i32 s53, s52, 31
	s_lshl_b64 s[0:1], s[52:53], 20
	s_add_u32 s62, s20, s0
	s_addc_u32 s63, s21, s1
	s_and_b64 s[0:1], s[6:7], exec
	s_cselect_b32 s22, s63, s77
	s_cselect_b32 s23, s62, s76
	s_ashr_i32 s51, s50, 31
	s_lshl_b64 s[0:1], s[50:51], 20
	s_add_u32 s84, s26, s0
	s_addc_u32 s85, s27, s1
	s_and_b64 s[0:1], s[6:7], exec
	s_cselect_b32 s41, s85, s91
	s_cselect_b32 s44, s84, s90
	s_lshl_b32 s64, s57, 8
	s_ashr_i32 s65, s64, 31
	s_lshl_b64 s[0:1], s[64:65], 2
	s_ashr_i32 s18, s40, 5
	v_lshl_add_u64 v[2:3], v[206:207], 0, s[0:1]
	v_lshl_add_u64 v[4:5], v[208:209], 0, s[0:1]
	v_mad_i64_i32 v[70:71], s[0:1], s18, v235, v[2:3]
	s_add_u32 s51, s90, 0x100
	v_mad_i64_i32 v[72:73], s[0:1], s18, v235, v[4:5]
	s_addc_u32 s53, s91, 0
	s_mov_b32 s57, -2
	s_branch .LBB0_510
	.p2align	6

.LBB0_580:
	s_ashr_i32 s47, s46, 31
	s_lshl_b64 s[0:1], s[46:47], 20
	s_add_u32 s48, s20, s0
	s_addc_u32 s49, s21, s1
	s_and_b64 s[0:1], s[6:7], exec
	s_cselect_b32 s22, s49, s63
	s_cselect_b32 s23, s48, s62
	s_ashr_i32 s39, s38, 31
	s_lshl_b64 s[0:1], s[38:39], 20
	s_add_u32 s50, s26, s0
	s_addc_u32 s51, s27, s1
	s_and_b64 s[0:1], s[6:7], exec
	s_cselect_b32 s39, s51, s65
	s_cselect_b32 s47, s50, s64
	s_ashr_i32 s53, s52, 31
	s_lshl_b32 s18, s44, 8
	s_lshl_b64 s[0:1], s[52:53], 10
	s_ashr_i32 s24, s52, 5
	s_ashr_i32 s19, s18, 31
	s_add_u32 s62, s62, 0x80080
	v_lshl_add_u64 v[2:3], s[18:19], 2, v[132:133]
	s_addc_u32 s63, s63, 0
	v_lshl_add_u64 v[140:141], v[134:135], 0, s[0:1]
	v_mad_i64_i32 v[142:143], s[0:1], s24, v236, v[2:3]
	s_add_u32 s53, s64, 0x100
	s_addc_u32 s58, s65, 0
	s_mov_b32 s76, -2
	s_branch .LBB0_582
	.p2align	6

.LBB0_644:
	s_lshl_b32 s6, s23, 8
	s_ashr_i32 s7, s6, 31
	s_lshl_b64 s[0:1], s[6:7], 2
	s_ashr_i32 s24, s22, 5
	v_lshl_add_u64 v[2:3], v[204:205], 0, s[0:1]
	v_mad_i64_i32 v[66:67], s[18:19], s24, v235, v[2:3]
	s_mul_hi_i32 s7, s24, 0xc000
	s_mul_i32 s24, s24, 0xc000
	s_add_u32 s18, s90, s24
	s_addc_u32 s7, s80, s7
	s_add_u32 s0, s18, s0
	s_addc_u32 s1, s7, s1
	s_add_u32 s7, s64, 0x100
	v_lshl_add_u64 v[68:69], s[0:1], 0, v[194:195]
	s_addc_u32 s23, s65, 0
	s_mov_b32 s41, -2
	s_branch .LBB0_646
	.p2align	6
